# speedup vs baseline: 1.0085x; 1.0085x over previous
; DI int ltid() { int x = threadIdx.x; asm volatile("" : "+v"(x)); return x; }
; DI int lbid() { int x = blockIdx.x; asm volatile("" : "+s"(x)); return x; }
; DI void cmp2_phase(const Params& p) {
;   const int tid = ltid(), nn = tid & 63, rr = tid >> 6;
;   for (int task = lbid(); task < 2048; task += gridDim.x) {
;     const int c = task >> 10, m = (task & 1023) * 4 + rr;
;     const u16* hrow = p.h1 + ((long)c * 4096 + m) * 256;
;     const float* w2 = p.a_w2_k; if (c) w2 = p.a_w2_v;
.LBB0_735:
	s_mov_b32 s98, 0
	v_mov_b32_e32 v0, v222
	s_mov_b32 s12, s43
	s_cmpk_gt_i32 s12, 0x7ff
	s_cbranch_scc1 .LBB0_744
	v_and_b32_e32 v6, 63, v0
	v_ashrrev_i32_e32 v0, 6, v0
	s_load_dword s13, s[56:57], 0x170
	s_load_dwordx2 s[0:1], s[56:57], 0x148
	s_load_dwordx2 s[2:3], s[56:57], 0x100
	v_mov_b32_e32 v1, 0xf00
	v_lshl_or_b32 v2, v6, 2, v1
	v_ashrrev_i32_e32 v1, 31, v0
	v_lshlrev_b64 v[4:5], 9, v[0:1]
	v_mbcnt_lo_u32_b32 v1, -1, 0
	v_mbcnt_hi_u32_b32 v1, -1, v1
	v_mov_b32_e32 v3, 0
	s_waitcnt lgkmcnt(0)
	v_lshl_add_u64 v[4:5], s[0:1], 0, v[4:5]
	v_and_b32_e32 v8, 64, v1
	v_cmp_eq_u32_e64 s[4:5], 0, v6
	v_lshl_add_u64 v[4:5], v[4:5], 0, 28
	s_lshl_b32 s14, s12, 2
	s_lshl_b32 s15, s13, 2
	s_mov_b64 s[10:11], 0x1000
	s_movk_i32 s16, 0x1ff
	s_movk_i32 s17, 0x150
	v_lshlrev_b32_e32 v6, 1, v6
	v_mov_b32_e32 v7, v3
	v_add_u32_e32 v12, 64, v8
	v_xor_b32_e32 v13, 32, v1
	v_xor_b32_e32 v14, 16, v1
	v_xor_b32_e32 v15, 8, v1
	v_xor_b32_e32 v16, 4, v1
	v_xor_b32_e32 v17, 2, v1
	v_xor_b32_e32 v18, 1, v1
	s_branch .LBB0_739

; DI float bflo(unsigned v) { return __uint_as_float(v << 16); }
; DI float bfhi(unsigned v) { return __uint_as_float(v & 0xffff0000u); }
; DI int lbid() { int x = blockIdx.x; asm volatile("" : "+s"(x)); return x; }
; DI void cmp2_phase(const Params& p) {
;     ...
;   for (int task = lbid(); task < 2048; task += gridDim.x) {
;     const int c = task >> 10, m = (task & 1023) * 4 + rr;
;     const u16* hrow = p.h1 + ((long)c * 4096 + m) * 256;
;     const float* w2 = p.a_w2_k; if (c) w2 = p.a_w2_v;
;     float s = 0.f;
;     for (int k = 0; k < 256; k += 2) {
;       const unsigned hv = *(const unsigned*)(hrow + k);
;       s += bflo(hv) * w2[k * 64 + nn] + bfhi(hv) * w2[(k + 1) * 64 + nn];
.LBB0_739:
	s_lshl_b32 s0, s14, 9
	s_and_b32 s20, s0, 0x1ff800
	s_ashr_i32 s0, s12, 10
	s_ashr_i32 s1, s0, 31
	s_lshl_b64 s[6:7], s[0:1], 21
	s_cmpk_lt_u32 s12, 0x400
	s_cselect_b64 s[0:1], -1, 0
	s_and_b64 s[18:19], s[0:1], exec
	s_cselect_b32 s18, 64, 0x50
	s_mov_b32 s99, s18
	s_add_u32 s18, s56, s18
	s_addc_u32 s19, s57, 0
	s_load_dwordx2 s[18:19], s[18:19], 0x0
	s_or_b32 s6, s6, s20
	v_lshl_add_u64 v[8:9], v[4:5], 0, s[6:7]
	s_mov_b32 s6, -2
	v_mov_b32_e32 v19, 0
	s_waitcnt lgkmcnt(0)
	s_cmp_eq_u32 s98, s99
	s_cbranch_scc1 .Lcmp2_have_w
	s_mov_b32 s98, s99
	s_barrier
	v_lshlrev_b32_e32 v97, 4, v222
	v_mov_b32_e32 v98, v97
	global_load_dwordx4 v[60:63], v98, s[18:19]
	v_add_u32_e32 v98, 0x1000, v97
	global_load_dwordx4 v[64:67], v98, s[18:19]
	v_add_u32_e32 v98, 0x2000, v97
	global_load_dwordx4 v[68:71], v98, s[18:19]
	v_add_u32_e32 v98, 0x3000, v97
	global_load_dwordx4 v[72:75], v98, s[18:19]
	s_waitcnt vmcnt(0)
	ds_write_b128 v97, v[60:63]
	ds_write_b128 v97, v[64:67] offset:4096
	ds_write_b128 v97, v[68:71] offset:8192
	ds_write_b128 v97, v[72:75] offset:12288
	v_add_u32_e32 v98, 0x4000, v97
	global_load_dwordx4 v[60:63], v98, s[18:19]
	v_add_u32_e32 v98, 0x5000, v97
	global_load_dwordx4 v[64:67], v98, s[18:19]
	v_add_u32_e32 v98, 0x6000, v97
	global_load_dwordx4 v[68:71], v98, s[18:19]
	v_add_u32_e32 v98, 0x7000, v97
	global_load_dwordx4 v[72:75], v98, s[18:19]
	s_waitcnt vmcnt(0)
	ds_write_b128 v97, v[60:63] offset:16384
	ds_write_b128 v97, v[64:67] offset:20480
	ds_write_b128 v97, v[68:71] offset:24576
	ds_write_b128 v97, v[72:75] offset:28672
	v_add_u32_e32 v98, 0x8000, v97
	global_load_dwordx4 v[60:63], v98, s[18:19]
	v_add_u32_e32 v98, 0x9000, v97
	global_load_dwordx4 v[64:67], v98, s[18:19]
	v_add_u32_e32 v98, 0xa000, v97
	global_load_dwordx4 v[68:71], v98, s[18:19]
	v_add_u32_e32 v98, 0xb000, v97
	global_load_dwordx4 v[72:75], v98, s[18:19]
	s_waitcnt vmcnt(0)
	ds_write_b128 v97, v[60:63] offset:32768
	ds_write_b128 v97, v[64:67] offset:36864
	ds_write_b128 v97, v[68:71] offset:40960
	ds_write_b128 v97, v[72:75] offset:45056
	v_add_u32_e32 v98, 0xc000, v97
	global_load_dwordx4 v[60:63], v98, s[18:19]
	v_add_u32_e32 v98, 0xd000, v97
	global_load_dwordx4 v[64:67], v98, s[18:19]
	v_add_u32_e32 v98, 0xe000, v97
	global_load_dwordx4 v[68:71], v98, s[18:19]
	v_add_u32_e32 v98, 0xf000, v97
	global_load_dwordx4 v[72:75], v98, s[18:19]
	s_waitcnt vmcnt(0)
	ds_write_b128 v97, v[60:63] offset:49152
	ds_write_b128 v97, v[64:67] offset:53248
	ds_write_b128 v97, v[68:71] offset:57344
	ds_write_b128 v97, v[72:75] offset:61440
	s_waitcnt lgkmcnt(0)
	s_barrier
.Lcmp2_have_w:
	v_add_u32_e32 v96, 0xfffff100, v2
; DI unsigned pack2(float a, float b) { v2f f = {a, b}; return __builtin_bit_cast(unsigned, __builtin_convertvector(f, v2bf)); }
; DI float bflo(unsigned v) { return __uint_as_float(v << 16); }
; DI float bfhi(unsigned v) { return __uint_as_float(v & 0xffff0000u); }
; DI void cmp2_phase(const Params& p) {
;     ...
;     for (int k = 0; k < 256; k += 2) {
;       const unsigned hv = *(const unsigned*)(hrow + k);
;       s += bflo(hv) * w2[k * 64 + nn] + bfhi(hv) * w2[(k + 1) * 64 + nn];
;     }
;     if ((m & 511) == 511) s = 0.f;
;     u16* dstp = p.kcmp; if (c) dstp = p.vcmp; dstp += (long)m * 64 + nn;
;     *dstp = (u16)(pack2(s, 0.f) & 0xffffu);
;     if (c == 0) {
;       float ss = s * s;
; #pragma unroll
;       for (int o = 32; o > 0; o >>= 1) ss += __shfl_xor(ss, o);
;       if (nn == 0) atomicMax(p.kmax2 + 480 + (m >> 9), __float_as_uint(ss));
;     }
.LBB0_740:
	global_load_dwordx4 v[20:23], v[8:9], off offset:-28
	global_load_dwordx4 v[24:27], v[8:9], off offset:-12
	ds_read_b32 v28, v96
	ds_read_b32 v29, v96 offset:256
	ds_read_b32 v30, v96 offset:512
	ds_read_b32 v31, v96 offset:768
	ds_read_b32 v32, v96 offset:1024
	ds_read_b32 v33, v96 offset:1280
	ds_read_b32 v34, v96 offset:1536
	ds_read_b32 v35, v96 offset:1792
	ds_read_b32 v36, v96 offset:2048
	ds_read_b32 v37, v96 offset:2304
	ds_read_b32 v38, v96 offset:2560
	ds_read_b32 v39, v96 offset:2816
	ds_read_b32 v40, v96 offset:3072
	ds_read_b32 v41, v96 offset:3328
	ds_read_b32 v42, v96 offset:3584
	ds_read_b32 v43, v96 offset:3840
	s_add_i32 s6, s6, 16
	v_add_u32_e32 v96, 0x1000, v96
	v_lshl_add_u64 v[8:9], v[8:9], 0, 32
	s_cmpk_gt_u32 s6, 0xfd
	s_waitcnt vmcnt(1)
	v_lshlrev_b32_e32 v44, 16, v20
	v_and_b32_e32 v45, 0xffff0000, v20
	v_lshlrev_b32_e32 v20, 16, v21
	v_and_b32_e32 v21, 0xffff0000, v21
	s_waitcnt vmcnt(0) lgkmcnt(14)
	v_pk_mul_f32 v[28:29], v[28:29], v[44:45]
	v_lshlrev_b32_e32 v46, 16, v22
	v_and_b32_e32 v47, 0xffff0000, v22
	s_waitcnt lgkmcnt(12)
	v_pk_mul_f32 v[20:21], v[30:31], v[20:21]
	v_add_f32_e32 v28, v28, v29
	v_lshlrev_b32_e32 v22, 16, v23
	v_and_b32_e32 v23, 0xffff0000, v23
	s_waitcnt lgkmcnt(10)
	v_pk_mul_f32 v[30:31], v[32:33], v[46:47]
	v_add_f32_e32 v20, v20, v21
	v_add_f32_e32 v19, v19, v28
	v_lshlrev_b32_e32 v48, 16, v24
	v_and_b32_e32 v49, 0xffff0000, v24
	s_waitcnt lgkmcnt(8)
	v_pk_mul_f32 v[22:23], v[34:35], v[22:23]
	v_add_f32_e32 v21, v30, v31
	v_add_f32_e32 v19, v19, v20
	v_lshlrev_b32_e32 v24, 16, v25
	v_and_b32_e32 v25, 0xffff0000, v25
	s_waitcnt lgkmcnt(6)
	v_pk_mul_f32 v[32:33], v[36:37], v[48:49]
	v_add_f32_e32 v22, v22, v23
	v_add_f32_e32 v19, v19, v21
	v_lshlrev_b32_e32 v50, 16, v26
	v_and_b32_e32 v51, 0xffff0000, v26
	s_waitcnt lgkmcnt(4)
	v_pk_mul_f32 v[24:25], v[38:39], v[24:25]
	v_add_f32_e32 v23, v32, v33
	v_add_f32_e32 v19, v19, v22
	v_lshlrev_b32_e32 v26, 16, v27
	v_and_b32_e32 v27, 0xffff0000, v27
	s_waitcnt lgkmcnt(2)
	v_pk_mul_f32 v[34:35], v[40:41], v[50:51]
	v_add_f32_e32 v24, v24, v25
	v_add_f32_e32 v19, v19, v23
	s_waitcnt lgkmcnt(0)
	v_pk_mul_f32 v[26:27], v[42:43], v[26:27]
	v_add_f32_e32 v25, v34, v35
	v_add_f32_e32 v19, v19, v24
	v_add_f32_e32 v26, v26, v27
	v_add_f32_e32 v19, v19, v25
	v_add_f32_e32 v19, v19, v26
	s_cbranch_scc0 .LBB0_740
	s_lshl_b32 s6, s12, 2
	s_and_b32 s6, s6, 0xffc
	s_and_b64 vcc, s[0:1], exec
	s_cselect_b32 s0, s17, 0x158
	s_add_u32 s0, s56, s0
	s_addc_u32 s1, s57, 0
	s_load_dwordx2 s[0:1], s[0:1], 0x0
	v_add_u32_e32 v8, s6, v0
	v_ashrrev_i32_e32 v9, 31, v8
	v_and_b32_e32 v10, 0x1ff, v8
	v_cmp_ne_u32_e64 s[6:7], s16, v10
	v_lshlrev_b64 v[20:21], 7, v[8:9]
	s_waitcnt lgkmcnt(0)
	v_lshl_add_u64 v[20:21], s[0:1], 0, v[20:21]
	v_cndmask_b32_e64 v10, 0, v19, s[6:7]
	v_lshl_add_u64 v[20:21], v[20:21], 0, v[6:7]
	v_cvt_pk_bf16_f32 v9, v10, s0
	global_store_short v[20:21], v9, off
	s_cbranch_vccz .LBB0_738
	v_cmp_lt_i32_e32 vcc, v13, v12
	v_mul_f32_e32 v9, v10, v10
	s_nop 0
	v_cndmask_b32_e32 v11, v1, v13, vcc
	v_lshlrev_b32_e32 v11, 2, v11
	ds_bpermute_b32 v9, v11, v9
	v_cmp_lt_i32_e32 vcc, v14, v12
	s_waitcnt lgkmcnt(0)
	v_fmac_f32_e32 v9, v10, v10
	v_cndmask_b32_e32 v11, v1, v14, vcc
	v_lshlrev_b32_e32 v10, 2, v11
	ds_bpermute_b32 v10, v10, v9
	v_cmp_lt_i32_e32 vcc, v15, v12
	s_waitcnt lgkmcnt(0)
	v_add_f32_e32 v9, v9, v10
	v_cndmask_b32_e32 v11, v1, v15, vcc
	v_lshlrev_b32_e32 v11, 2, v11
	ds_bpermute_b32 v10, v11, v9
	v_cmp_lt_i32_e32 vcc, v16, v12
	s_waitcnt lgkmcnt(0)
	v_add_f32_e32 v9, v9, v10
	v_cndmask_b32_e32 v11, v1, v16, vcc
	v_lshlrev_b32_e32 v11, 2, v11
	ds_bpermute_b32 v10, v11, v9
	v_cmp_lt_i32_e32 vcc, v17, v12
	s_waitcnt lgkmcnt(0)
	v_add_f32_e32 v9, v9, v10
	v_cndmask_b32_e32 v11, v1, v17, vcc
	v_lshlrev_b32_e32 v11, 2, v11
	ds_bpermute_b32 v10, v11, v9
	v_cmp_lt_i32_e32 vcc, v18, v12
	s_waitcnt lgkmcnt(0)
	v_add_f32_e32 v9, v9, v10
	v_cndmask_b32_e32 v11, v1, v18, vcc
	v_lshlrev_b32_e32 v10, 2, v11
	ds_bpermute_b32 v10, v10, v9
	s_and_saveexec_b64 s[0:1], s[4:5]
	s_cbranch_execz .LBB0_737
	v_ashrrev_i32_e32 v20, 9, v8
	v_ashrrev_i32_e32 v21, 31, v20
	s_waitcnt lgkmcnt(0)
	v_add_f32_e32 v10, v9, v10
	v_lshl_add_u64 v[8:9], v[20:21], 2, s[2:3]
	global_load_dword v20, v[8:9], off offset:1920 sc1
	s_waitcnt vmcnt(0)
	v_cmp_gt_u32_e32 vcc, v10, v20
	s_and_b64 exec, exec, vcc
	s_cbranch_execz .LBB0_737
	global_atomic_umax v[8:9], v10, off offset:1920
	s_branch .LBB0_737
